# prologue rmsnorm row loop: DPP wave reductions instead of ds_bpermute chains (9 sums per row), loop-invariant dt-bias load hoisted out of the loop
# baseline (speedup 1.0000x reference)
.LBB0_304:
	s_or_b64 exec, exec, s[4:5]
	v_readlane_b32 s0, v253, 7
	s_cmp_lt_i32 s0, 0x8000
	s_waitcnt lgkmcnt(0)
	s_barrier
	v_readlane_b32 s1, v253, 8
	s_cbranch_scc0 .LBB0_313
	s_load_dwordx2 s[34:35], s[92:93], 0x0
	v_readlane_b32 s36, v253, 7
	v_readlane_b32 s37, v253, 8
	s_ashr_i32 s37, s36, 31
	s_lshl_b64 s[0:1], s[36:37], 12
	s_waitcnt lgkmcnt(0)
	s_add_u32 s0, s34, s0
	v_lshlrev_b32_e32 v122, 4, v168
	s_addc_u32 s1, s35, s1
	global_load_dwordx4 v[158:161], v122, s[0:1]
	global_load_dwordx4 v[154:157], v122, s[0:1] offset:1024
	global_load_dwordx4 v[150:153], v122, s[0:1] offset:2048
	global_load_dwordx4 v[146:149], v122, s[0:1] offset:3072
	v_mbcnt_lo_u32_b32 v1, -1, 0
	v_mbcnt_hi_u32_b32 v2, -1, v1
	v_and_b32_e32 v1, 64, v2
	v_add_u32_e32 v3, 64, v1
	v_xor_b32_e32 v1, 1, v2
	v_cmp_lt_i32_e32 vcc, v1, v3
	v_xor_b32_e32 v4, 2, v2
	v_lshl_add_u32 v126, v168, 7, 0
	v_cndmask_b32_e32 v1, v2, v1, vcc
	v_cmp_lt_i32_e32 vcc, v4, v3
	v_mov_b32_e32 v123, 0
	s_lshl_b64 s[0:1], s[36:37], 5
	v_cndmask_b32_e32 v4, v2, v4, vcc
	v_lshlrev_b32_e32 v171, 2, v4
	v_xor_b32_e32 v4, 4, v2
	v_cmp_lt_i32_e32 vcc, v4, v3
	v_lshlrev_b32_e32 v124, 2, v168
	v_mov_b32_e32 v125, v123
	v_cndmask_b32_e32 v4, v2, v4, vcc
	v_lshlrev_b32_e32 v177, 2, v4
	v_xor_b32_e32 v4, 8, v2
	v_cmp_lt_i32_e32 vcc, v4, v3
	v_lshl_add_u64 v[124:125], s[0:1], 0, v[124:125]
	s_mov_b64 s[0:1], 0x3c2a000
	v_cndmask_b32_e32 v4, v2, v4, vcc
	v_lshlrev_b32_e32 v178, 2, v4
	v_xor_b32_e32 v4, 16, v2
	v_cmp_lt_i32_e32 vcc, v4, v3
	v_lshl_add_u64 v[164:165], v[124:125], 0, s[0:1]
	s_lshl_b64 s[0:1], s[36:37], 11
	v_cndmask_b32_e32 v4, v2, v4, vcc
	v_lshlrev_b32_e32 v179, 2, v4
	v_xor_b32_e32 v4, 32, v2
	v_cmp_lt_i32_e32 vcc, v4, v3
	v_lshl_or_b32 v166, v168, 3, s0
	s_add_i32 s0, s36, s78
	v_cndmask_b32_e32 v2, v2, v4, vcc
	v_lshlrev_b32_e32 v180, 2, v2
	ds_read_b128 v[2:5], v126
	ds_read_b128 v[6:9], v126 offset:16
	ds_read_b128 v[10:13], v126 offset:32
	ds_read_b128 v[14:17], v126 offset:48
	ds_read_b128 v[18:21], v126 offset:64
	ds_read_b128 v[22:25], v126 offset:80
	ds_read_b128 v[26:29], v126 offset:96
	ds_read_b128 v[30:33], v126 offset:112
	ds_read_b128 v[34:37], v126 offset:8192
	ds_read_b128 v[38:41], v126 offset:8208
	ds_read_b128 v[42:45], v126 offset:8224
	ds_read_b128 v[46:49], v126 offset:8240
	ds_read_b128 v[50:53], v126 offset:8256
	ds_read_b128 v[54:57], v126 offset:8272
	ds_read_b128 v[58:61], v126 offset:8288
	ds_read_b128 v[62:65], v126 offset:8304
	ds_read_b128 v[66:69], v126 offset:16384
	ds_read_b128 v[70:73], v126 offset:16400
	ds_read_b128 v[74:77], v126 offset:16416
	ds_read_b128 v[78:81], v126 offset:16432
	ds_read_b128 v[82:85], v126 offset:16448
	ds_read_b128 v[86:89], v126 offset:16464
	ds_read_b128 v[90:93], v126 offset:16480
	ds_read_b128 v[94:97], v126 offset:16496
	ds_read_b128 v[98:101], v126 offset:24576
	ds_read_b128 v[102:105], v126 offset:24592
	ds_read_b128 v[106:109], v126 offset:24608
	ds_read_b128 v[110:113], v126 offset:24624
	ds_read_b128 v[114:117], v126 offset:24640
	ds_read_b128 v[118:121], v126 offset:24656
	s_ashr_i32 s79, s78, 31
	v_mov_b32_e32 v167, s1
	s_ashr_i32 s1, s0, 31
	s_lshl_b64 s[4:5], s[78:79], 5
	s_lshl_b64 s[30:31], s[78:79], 11
	s_lshl_b64 s[0:1], s[0:1], 12
	s_add_u32 s0, s34, s0
	s_addc_u32 s1, s35, s1
	v_lshl_add_u64 v[172:173], s[0:1], 0, v[122:123]
	ds_read_b128 v[122:125], v126 offset:24672
	ds_read_b128 v[126:129], v126 offset:24688
	s_mov_b32 s38, s36
	v_lshlrev_b32_e32 v1, 2, v1
	v_cmp_gt_u32_e64 s[6:7], 8, v168
	v_cmp_eq_u32_e64 s[8:9], 7, v168
	v_cmp_eq_u32_e64 s[10:11], 6, v168
	v_cmp_eq_u32_e64 s[12:13], 5, v168
	v_cmp_eq_u32_e64 s[14:15], 4, v168
	v_cmp_eq_u32_e64 s[16:17], 3, v168
	v_cmp_eq_u32_e64 s[18:19], 2, v168
	v_cmp_eq_u32_e64 s[20:21], 1, v168
	v_cmp_eq_u32_e64 s[22:23], 0, v168
	s_lshl_b64 s[34:35], s[78:79], 12
	s_movk_i32 s0, 0x7fff
	v_mov_b32_e32 v181, 0x358637bd
	s_mov_b32 s1, 0xffff0000
	s_mov_b32 s33, 0x4400000
	v_lshlrev_b32_e32 v182, 2, v168
	s_mov_b32 s42, 0x41a00000
	s_mov_b32 s43, 0x3fb8aa3b
	s_mov_b32 s44, 0xc2ce8ed0
	s_mov_b32 s45, 0x42b17218
	s_mov_b32 s46, 0x7f800000
	s_mov_b32 s47, 0x3f2aaaab
	v_mov_b32_e32 v183, 0x3ecc95a3
	s_mov_b32 s48, 0x3f317218
	s_mov_b32 s49, 0x33800000
	s_waitcnt vmcnt(3)
	v_mov_b64_e32 v[142:143], v[158:159]
	s_waitcnt vmcnt(2)
	v_mov_b64_e32 v[138:139], v[154:155]
	s_waitcnt vmcnt(1)
	v_mov_b64_e32 v[134:135], v[150:151]
	s_waitcnt vmcnt(0)
	v_mov_b64_e32 v[130:131], v[146:147]
	v_mov_b32_e32 v184, 0x7f800000
	v_mov_b32_e32 v174, 0x3f317218
	v_writelane_b32 v253, s38, 7
	s_mov_b32 s50, s36
	v_mov_b64_e32 v[132:133], v[148:149]
	v_mov_b64_e32 v[136:137], v[152:153]
	v_mov_b64_e32 v[140:141], v[156:157]
	v_mov_b64_e32 v[144:145], v[160:161]
	v_writelane_b32 v253, s39, 8
	s_load_dwordx2 s[66:67], s[92:93], 0x28
	s_and_saveexec_b64 s[68:69], s[6:7]
	s_waitcnt lgkmcnt(0)
	global_load_dword v196, v182, s[66:67]
	s_waitcnt vmcnt(0)
	s_mov_b64 exec, s[68:69]
	s_branch .LBB0_308

.LBB0_310:
	v_mul_f32_e32 v175, v159, v159
	s_waitcnt lgkmcnt(0)
	v_mul_f32_e32 v176, v161, v161
	v_fmac_f32_e32 v175, v158, v158
	v_fmac_f32_e32 v176, v160, v160
	v_add_f32_e32 v175, v175, v176
	v_mul_f32_e32 v176, v155, v155
	v_mul_f32_e32 v185, v157, v157
	v_fmac_f32_e32 v176, v154, v154
	v_fmac_f32_e32 v185, v156, v156
	v_add_f32_e32 v176, v176, v185
	v_add_f32_e32 v175, v176, v175
	v_mul_f32_e32 v176, v151, v151
	v_mul_f32_e32 v185, v153, v153
	v_fmac_f32_e32 v176, v150, v150
	v_fmac_f32_e32 v185, v152, v152
	v_add_f32_e32 v176, v176, v185
	v_add_f32_e32 v175, v176, v175
	v_mul_f32_e32 v176, v147, v147
	v_mul_f32_e32 v185, v149, v149
	v_fmac_f32_e32 v176, v146, v146
	v_fmac_f32_e32 v185, v148, v148
	v_add_f32_e32 v176, v176, v185
	v_add_f32_e32 v175, v176, v175
	v_lshl_add_u64 v[186:187], s[28:29], 0, v[166:167]
	s_nop 0
	v_add_f32_dpp v175, v175, v175 quad_perm:[1,0,3,2] row_mask:0xf bank_mask:0xf
	s_nop 1
	v_add_f32_dpp v175, v175, v175 quad_perm:[2,3,0,1] row_mask:0xf bank_mask:0xf
	s_nop 1
	v_add_f32_dpp v175, v175, v175 row_half_mirror row_mask:0xf bank_mask:0xf
	s_nop 1
	v_add_f32_dpp v175, v175, v175 row_mirror row_mask:0xf bank_mask:0xf
	s_nop 1
	v_readlane_b32 s66, v175, 0
	v_readlane_b32 s67, v175, 16
	v_readlane_b32 s68, v175, 32
	v_readlane_b32 s69, v175, 48
	v_mov_b32_e32 v175, s66
	v_add_f32_e32 v175, s67, v175
	v_mov_b32_e32 v176, s68
	v_add_f32_e32 v176, s69, v176
	v_add_f32_e32 v175, v175, v176
	v_fmamk_f32 v175, v175, 0x3a800000, v181
	v_rsq_f32_e32 v176, v175
	s_nop 0
	v_pk_mul_f32 v[188:189], v[158:159], v[176:177] op_sel_hi:[1,0]
	v_pk_mul_f32 v[160:161], v[160:161], v[176:177] op_sel_hi:[1,0]
	v_bfe_u32 v158, v188, 16, 1
	v_bfe_u32 v159, v189, 16, 1
	v_bfe_u32 v175, v160, 16, 1
	v_add3_u32 v158, v188, v158, s0
	v_bfe_u32 v185, v161, 16, 1
	v_add3_u32 v159, v189, v159, s0
	v_add3_u32 v175, v160, v175, s0
	v_lshrrev_b32_e32 v158, 16, v158
	v_add3_u32 v185, v161, v185, s0
	v_lshrrev_b32_e32 v175, 16, v175
	v_and_or_b32 v190, v159, s1, v158
	v_add_co_u32_e32 v158, vcc, s33, v186
	v_and_or_b32 v191, v185, s1, v175
	s_nop 0
	v_addc_co_u32_e32 v159, vcc, 0, v187, vcc
	global_store_dwordx2 v[158:159], v[190:191], off
	v_fma_f32 v190, v3, v188, 0
	v_fmac_f32_e32 v190, v11, v189
	v_fmac_f32_e32 v190, v19, v160
	v_fma_f32 v175, v2, v188, 0
	v_fma_f32 v185, v6, v188, 0
	v_fma_f32 v191, v7, v188, 0
	v_fma_f32 v192, v4, v188, 0
	v_fma_f32 v193, v8, v188, 0
	v_fma_f32 v194, v5, v188, 0
	v_fma_f32 v195, v9, v188, 0
	v_fmac_f32_e32 v190, v161, v27
	v_pk_mul_f32 v[154:155], v[154:155], v[176:177] op_sel_hi:[1,0]
	v_fmac_f32_e32 v175, v10, v189
	v_fmac_f32_e32 v185, v14, v189
	v_fmac_f32_e32 v191, v15, v189
	v_fmac_f32_e32 v192, v12, v189
	v_fmac_f32_e32 v193, v16, v189
	v_fmac_f32_e32 v194, v13, v189
	v_fmac_f32_e32 v195, v17, v189
	v_fmac_f32_e32 v190, v154, v35
	v_fmac_f32_e32 v175, v18, v160
	v_fmac_f32_e32 v185, v22, v160
	v_fmac_f32_e32 v191, v23, v160
	v_fmac_f32_e32 v192, v20, v160
	v_fmac_f32_e32 v193, v24, v160
	v_fmac_f32_e32 v194, v21, v160
	v_fmac_f32_e32 v195, v25, v160
	v_pk_mul_f32 v[156:157], v[156:157], v[176:177] op_sel_hi:[1,0]
	v_bfe_u32 v160, v154, 16, 1
	v_fmac_f32_e32 v190, v155, v43
	v_fmac_f32_e32 v175, v161, v26
	v_fmac_f32_e32 v185, v161, v30
	v_fmac_f32_e32 v191, v161, v31
	v_fmac_f32_e32 v192, v161, v28
	v_fmac_f32_e32 v193, v161, v32
	v_fmac_f32_e32 v194, v161, v29
	v_fmac_f32_e32 v195, v161, v33
	v_add3_u32 v160, v154, v160, s0
	v_bfe_u32 v161, v155, 16, 1
	v_fmac_f32_e32 v190, v156, v51
	v_lshrrev_b32_e32 v160, 16, v160
	v_add3_u32 v161, v155, v161, s0
	v_fmac_f32_e32 v190, v157, v59
	v_pk_mul_f32 v[150:151], v[150:151], v[176:177] op_sel_hi:[1,0]
	v_and_or_b32 v160, v161, s1, v160
	v_bfe_u32 v161, v156, 16, 1
	v_fmac_f32_e32 v190, v150, v67
	v_add3_u32 v161, v156, v161, s0
	v_bfe_u32 v186, v157, 16, 1
	v_pk_mul_f32 v[152:153], v[152:153], v[176:177] op_sel_hi:[1,0]
	v_fmac_f32_e32 v190, v151, v75
	v_lshrrev_b32_e32 v161, 16, v161
	v_add3_u32 v186, v157, v186, s0
	v_fmac_f32_e32 v190, v152, v83
	v_pk_mul_f32 v[146:147], v[146:147], v[176:177] op_sel_hi:[1,0]
	v_and_or_b32 v161, v186, s1, v161
	v_fmac_f32_e32 v190, v153, v91
	v_pk_mul_f32 v[186:187], v[148:149], v[176:177] op_sel_hi:[1,0]
	v_bfe_u32 v148, v146, 16, 1
	v_add3_u32 v148, v146, v148, s0
	v_bfe_u32 v149, v147, 16, 1
	v_fmac_f32_e32 v190, v146, v99
	v_lshrrev_b32_e32 v148, 16, v148
	v_add3_u32 v149, v147, v149, s0
	v_fmac_f32_e32 v190, v147, v107
	v_and_or_b32 v188, v149, s1, v148
	v_bfe_u32 v148, v186, 16, 1
	v_fmac_f32_e32 v190, v186, v115
	v_fmac_f32_e32 v192, v154, v36
	v_add3_u32 v148, v186, v148, s0
	v_fmac_f32_e32 v190, v187, v123
	v_fmac_f32_e32 v192, v155, v44
	v_lshrrev_b32_e32 v189, 16, v148
	v_fmac_f32_e32 v192, v156, v52
	v_fmac_f32_e32 v192, v157, v60
	v_fmac_f32_e32 v192, v150, v68
	v_fmac_f32_e32 v192, v151, v76
	v_fmac_f32_e32 v192, v152, v84
	v_fmac_f32_e32 v192, v153, v92
	v_fmac_f32_e32 v175, v154, v34
	v_fmac_f32_e32 v185, v154, v38
	v_fmac_f32_e32 v191, v154, v39
	v_fmac_f32_e32 v193, v154, v40
	v_fmac_f32_e32 v194, v154, v37
	v_fmac_f32_e32 v195, v154, v41
	v_fmac_f32_e32 v192, v146, v100
	v_fmac_f32_e32 v175, v155, v42
	v_fmac_f32_e32 v185, v155, v46
	v_fmac_f32_e32 v191, v155, v47
	v_fmac_f32_e32 v193, v155, v48
	v_fmac_f32_e32 v194, v155, v45
	v_fmac_f32_e32 v195, v155, v49
	v_fmac_f32_e32 v192, v147, v108
	v_fmac_f32_e32 v175, v156, v50
	v_fmac_f32_e32 v185, v156, v54
	v_fmac_f32_e32 v191, v156, v55
	v_fmac_f32_e32 v193, v156, v56
	v_fmac_f32_e32 v194, v156, v53
	v_fmac_f32_e32 v195, v156, v57
	v_fmac_f32_e32 v192, v186, v116
	v_fmac_f32_e32 v175, v157, v58
	v_fmac_f32_e32 v185, v157, v62
	v_fmac_f32_e32 v191, v157, v63
	v_fmac_f32_e32 v193, v157, v64
	v_fmac_f32_e32 v194, v157, v61
	v_fmac_f32_e32 v195, v157, v65
	v_bfe_u32 v154, v150, 16, 1
	v_fmac_f32_e32 v192, v187, v124
	v_add3_u32 v154, v150, v154, s0
	v_fmac_f32_e32 v175, v150, v66
	v_fmac_f32_e32 v185, v150, v70
	v_fmac_f32_e32 v191, v150, v71
	v_fmac_f32_e32 v193, v150, v72
	v_fmac_f32_e32 v194, v150, v69
	v_fmac_f32_e32 v195, v150, v73
	v_bfe_u32 v155, v151, 16, 1
	v_fmac_f32_e32 v185, v151, v78
	v_fmac_f32_e32 v194, v151, v77
	v_add3_u32 v155, v151, v155, s0
	v_fmac_f32_e32 v175, v151, v74
	v_fmac_f32_e32 v191, v151, v79
	v_fmac_f32_e32 v193, v151, v80
	v_fmac_f32_e32 v195, v151, v81
	v_fmac_f32_e32 v185, v152, v86
	v_fmac_f32_e32 v194, v152, v85
	v_fmac_f32_e32 v185, v153, v94
	v_fmac_f32_e32 v194, v153, v93
	v_fmac_f32_e32 v185, v146, v102
	v_fmac_f32_e32 v194, v146, v101
	v_fmac_f32_e32 v185, v147, v110
	v_fmac_f32_e32 v194, v147, v109
	v_lshrrev_b32_e32 v154, 16, v154
	v_fmac_f32_e32 v185, v186, v118
	v_fmac_f32_e32 v194, v186, v117
	v_and_or_b32 v154, v155, s1, v154
	v_bfe_u32 v155, v152, 16, 1
	v_fmac_f32_e32 v185, v187, v126
	v_fmac_f32_e32 v194, v187, v125
	v_add3_u32 v155, v152, v155, s0
	v_fmac_f32_e32 v175, v152, v82
	v_fmac_f32_e32 v191, v152, v87
	v_fmac_f32_e32 v193, v152, v88
	v_fmac_f32_e32 v195, v152, v89
	v_bfe_u32 v156, v153, 16, 1
	v_lshrrev_b32_e32 v155, 16, v155
	v_add3_u32 v156, v153, v156, s0
	v_and_or_b32 v155, v156, s1, v155
	global_store_dwordx2 v[158:159], v[154:155], off offset:1024
	v_fmac_f32_e32 v175, v153, v90
	v_fmac_f32_e32 v191, v153, v95
	v_fmac_f32_e32 v193, v153, v96
	v_fmac_f32_e32 v195, v153, v97
	v_fmac_f32_e32 v175, v146, v98
	v_fmac_f32_e32 v191, v146, v103
	v_fmac_f32_e32 v193, v146, v104
	v_fmac_f32_e32 v195, v146, v105
	v_fmac_f32_e32 v175, v147, v106
	v_fmac_f32_e32 v191, v147, v111
	v_fmac_f32_e32 v193, v147, v112
	v_fmac_f32_e32 v195, v147, v113
	v_fmac_f32_e32 v175, v186, v114
	v_fmac_f32_e32 v191, v186, v119
	v_fmac_f32_e32 v193, v186, v120
	v_fmac_f32_e32 v195, v186, v121
	v_fmac_f32_e32 v175, v187, v122
	v_fmac_f32_e32 v191, v187, v127
	v_fmac_f32_e32 v193, v187, v128
	v_fmac_f32_e32 v195, v187, v129
	s_nop 1
	v_add_f32_dpp v175, v175, v175 quad_perm:[1,0,3,2] row_mask:0xf bank_mask:0xf
	v_add_f32_dpp v190, v190, v190 quad_perm:[1,0,3,2] row_mask:0xf bank_mask:0xf
	v_add_f32_dpp v192, v192, v192 quad_perm:[1,0,3,2] row_mask:0xf bank_mask:0xf
	v_add_f32_dpp v194, v194, v194 quad_perm:[1,0,3,2] row_mask:0xf bank_mask:0xf
	v_add_f32_dpp v185, v185, v185 quad_perm:[1,0,3,2] row_mask:0xf bank_mask:0xf
	v_add_f32_dpp v191, v191, v191 quad_perm:[1,0,3,2] row_mask:0xf bank_mask:0xf
	v_add_f32_dpp v193, v193, v193 quad_perm:[1,0,3,2] row_mask:0xf bank_mask:0xf
	v_add_f32_dpp v195, v195, v195 quad_perm:[1,0,3,2] row_mask:0xf bank_mask:0xf
	v_add_f32_dpp v175, v175, v175 quad_perm:[2,3,0,1] row_mask:0xf bank_mask:0xf
	v_add_f32_dpp v190, v190, v190 quad_perm:[2,3,0,1] row_mask:0xf bank_mask:0xf
	v_add_f32_dpp v192, v192, v192 quad_perm:[2,3,0,1] row_mask:0xf bank_mask:0xf
	v_add_f32_dpp v194, v194, v194 quad_perm:[2,3,0,1] row_mask:0xf bank_mask:0xf
	v_add_f32_dpp v185, v185, v185 quad_perm:[2,3,0,1] row_mask:0xf bank_mask:0xf
	v_add_f32_dpp v191, v191, v191 quad_perm:[2,3,0,1] row_mask:0xf bank_mask:0xf
	v_add_f32_dpp v193, v193, v193 quad_perm:[2,3,0,1] row_mask:0xf bank_mask:0xf
	v_add_f32_dpp v195, v195, v195 quad_perm:[2,3,0,1] row_mask:0xf bank_mask:0xf
	v_add_f32_dpp v175, v175, v175 row_half_mirror row_mask:0xf bank_mask:0xf
	v_add_f32_dpp v190, v190, v190 row_half_mirror row_mask:0xf bank_mask:0xf
	v_add_f32_dpp v192, v192, v192 row_half_mirror row_mask:0xf bank_mask:0xf
	v_add_f32_dpp v194, v194, v194 row_half_mirror row_mask:0xf bank_mask:0xf
	v_add_f32_dpp v185, v185, v185 row_half_mirror row_mask:0xf bank_mask:0xf
	v_add_f32_dpp v191, v191, v191 row_half_mirror row_mask:0xf bank_mask:0xf
	v_add_f32_dpp v193, v193, v193 row_half_mirror row_mask:0xf bank_mask:0xf
	v_add_f32_dpp v195, v195, v195 row_half_mirror row_mask:0xf bank_mask:0xf
	v_add_f32_dpp v175, v175, v175 row_mirror row_mask:0xf bank_mask:0xf
	v_add_f32_dpp v190, v190, v190 row_mirror row_mask:0xf bank_mask:0xf
	v_add_f32_dpp v192, v192, v192 row_mirror row_mask:0xf bank_mask:0xf
	v_add_f32_dpp v194, v194, v194 row_mirror row_mask:0xf bank_mask:0xf
	v_add_f32_dpp v185, v185, v185 row_mirror row_mask:0xf bank_mask:0xf
	v_add_f32_dpp v191, v191, v191 row_mirror row_mask:0xf bank_mask:0xf
	v_add_f32_dpp v193, v193, v193 row_mirror row_mask:0xf bank_mask:0xf
	v_add_f32_dpp v195, v195, v195 row_mirror row_mask:0xf bank_mask:0xf
	v_add_f32_dpp v175, v175, v175 row_bcast:15 row_mask:0xa bank_mask:0xf
	v_add_f32_dpp v190, v190, v190 row_bcast:15 row_mask:0xa bank_mask:0xf
	v_add_f32_dpp v192, v192, v192 row_bcast:15 row_mask:0xa bank_mask:0xf
	v_add_f32_dpp v194, v194, v194 row_bcast:15 row_mask:0xa bank_mask:0xf
	v_add_f32_dpp v185, v185, v185 row_bcast:15 row_mask:0xa bank_mask:0xf
	v_add_f32_dpp v191, v191, v191 row_bcast:15 row_mask:0xa bank_mask:0xf
	v_add_f32_dpp v193, v193, v193 row_bcast:15 row_mask:0xa bank_mask:0xf
	v_add_f32_dpp v195, v195, v195 row_bcast:15 row_mask:0xa bank_mask:0xf
	v_add_f32_dpp v175, v175, v175 row_bcast:31 row_mask:0xc bank_mask:0xf
	v_add_f32_dpp v190, v190, v190 row_bcast:31 row_mask:0xc bank_mask:0xf
	v_add_f32_dpp v192, v192, v192 row_bcast:31 row_mask:0xc bank_mask:0xf
	v_add_f32_dpp v194, v194, v194 row_bcast:31 row_mask:0xc bank_mask:0xf
	v_add_f32_dpp v185, v185, v185 row_bcast:31 row_mask:0xc bank_mask:0xf
	v_add_f32_dpp v191, v191, v191 row_bcast:31 row_mask:0xc bank_mask:0xf
	v_add_f32_dpp v193, v193, v193 row_bcast:31 row_mask:0xc bank_mask:0xf
	v_add_f32_dpp v195, v195, v195 row_bcast:31 row_mask:0xc bank_mask:0xf
	s_nop 1
	v_readlane_b32 s66, v175, 63
	v_readlane_b32 s67, v190, 63
	v_readlane_b32 s68, v192, 63
	v_readlane_b32 s69, v194, 63
	v_readlane_b32 s76, v185, 63
	v_readlane_b32 s77, v191, 63
	v_readlane_b32 s80, v193, 63
	v_readlane_b32 s81, v195, 63
	global_store_dwordx2 v[158:159], v[160:161], off offset:512
	v_bfe_u32 v185, v187, 16, 1
	v_add3_u32 v185, v187, v185, s0
	v_and_or_b32 v189, v185, s1, v189
	global_store_dwordx2 v[158:159], v[188:189], off offset:1536
	s_and_saveexec_b64 s[38:39], s[6:7]
	s_cbranch_execz .LBB0_307
	v_writelane_b32 v146, s66, 0
	v_writelane_b32 v146, s67, 1
	v_writelane_b32 v146, s68, 2
	v_writelane_b32 v146, s69, 3
	v_writelane_b32 v146, s76, 4
	v_writelane_b32 v146, s77, 5
	v_writelane_b32 v146, s80, 6
	v_writelane_b32 v146, s81, 7
	v_add_f32_e32 v146, v146, v196
	v_cmp_nlt_f32_e32 vcc, s42, v146
	s_and_saveexec_b64 s[40:41], vcc
	s_cbranch_execz .LBB0_306
	v_mul_f32_e32 v147, 0x3fb8aa3b, v146
	v_rndne_f32_e32 v148, v147
	v_sub_f32_e32 v149, v147, v148
	v_fma_f32 v147, v146, s43, -v147
	v_fmac_f32_e32 v147, 0x32a5705f, v146
	v_add_f32_e32 v147, v149, v147
	v_cvt_i32_f32_e32 v148, v148
	v_exp_f32_e32 v147, v147
	v_cmp_ngt_f32_e32 vcc, s44, v146
	v_ldexp_f32 v147, v147, v148
	s_nop 0
	v_cndmask_b32_e32 v147, 0, v147, vcc
	v_cmp_nlt_f32_e32 vcc, s45, v146
	s_nop 1
	v_cndmask_b32_e32 v160, v184, v147, vcc
	v_add_f32_e32 v148, 1.0, v160
	v_add_f32_e32 v146, -1.0, v148
	v_sub_f32_e32 v147, v146, v148
	v_add_f32_e32 v147, 1.0, v147
	v_sub_f32_e32 v146, v160, v146
	v_add_f32_e32 v149, v146, v147
	v_frexp_mant_f32_e32 v150, v148
	v_cvt_f64_f32_e32 v[146:147], v148
	v_frexp_exp_i32_f64_e32 v146, v[146:147]
	v_cmp_gt_f32_e32 vcc, s47, v150
	s_nop 1
	v_subbrev_co_u32_e32 v154, vcc, 0, v146, vcc
	v_sub_u32_e32 v146, 0, v154
	v_ldexp_f32 v147, v148, v146
	v_add_f32_e32 v148, -1.0, v147
	v_add_f32_e32 v150, 1.0, v147
	v_ldexp_f32 v146, v149, v146
	v_add_f32_e32 v149, 1.0, v148
	v_add_f32_e32 v151, -1.0, v150
	v_sub_f32_e32 v149, v147, v149
	v_sub_f32_e32 v147, v147, v151
	v_add_f32_e32 v149, v146, v149
	v_add_f32_e32 v146, v146, v147
	v_add_f32_e32 v155, v150, v146
	v_rcp_f32_e32 v157, v155
	v_sub_f32_e32 v147, v150, v155
	v_add_f32_e32 v156, v146, v147
	v_add_f32_e32 v147, v148, v149
	v_mul_f32_e32 v159, v147, v157
	v_sub_f32_e32 v146, v148, v147
	v_mul_f32_e32 v148, v155, v159
	v_fma_f32 v150, v159, v155, -v148
	v_fmac_f32_e32 v150, v159, v156
	v_add_f32_e32 v158, v149, v146
	v_add_f32_e32 v146, v148, v150
	v_sub_f32_e32 v149, v147, v146
	v_pk_add_f32 v[152:153], v[146:147], v[148:149] neg_lo:[0,1] neg_hi:[0,1]
	v_mov_b32_e32 v151, v146
	v_pk_add_f32 v[146:147], v[152:153], v[150:151] neg_lo:[0,1] neg_hi:[0,1]
	v_cmp_neq_f32_e32 vcc, s46, v160
	v_add_f32_e32 v147, v158, v147
	v_add_f32_e32 v146, v146, v147
	v_add_f32_e32 v147, v149, v146
	v_mul_f32_e32 v158, v157, v147
	v_mul_f32_e32 v148, v155, v158
	v_fma_f32 v150, v158, v155, -v148
	v_fmac_f32_e32 v150, v158, v156
	v_sub_f32_e32 v149, v149, v147
	v_add_f32_e32 v155, v146, v149
	v_add_f32_e32 v146, v148, v150
	v_sub_f32_e32 v149, v147, v146
	v_pk_add_f32 v[152:153], v[146:147], v[148:149] neg_lo:[0,1] neg_hi:[0,1]
	v_mov_b32_e32 v151, v146
	v_pk_add_f32 v[146:147], v[152:153], v[150:151] neg_lo:[0,1] neg_hi:[0,1]
	s_nop 0
	v_add_f32_e32 v147, v155, v147
	v_add_f32_e32 v146, v146, v147
	v_add_f32_e32 v147, v159, v158
	v_add_f32_e32 v146, v149, v146
	v_sub_f32_e32 v148, v147, v159
	v_mul_f32_e32 v146, v157, v146
	v_sub_f32_e32 v148, v158, v148
	v_add_f32_e32 v148, v148, v146
	v_add_f32_e32 v150, v147, v148
	v_mul_f32_e32 v151, v150, v150
	v_fmamk_f32 v146, v151, 0x3e9b6dac, v183
	v_fmaak_f32 v175, v151, v146, 0x3f2aaada
	v_cvt_f32_i32_e32 v146, v154
	v_sub_f32_e32 v147, v150, v147
	v_sub_f32_e32 v147, v148, v147
	v_ldexp_f32 v152, v147, 1
	v_mul_f32_e32 v147, v150, v151
	v_ldexp_f32 v149, v150, 1
	v_pk_mul_f32 v[150:151], v[146:147], v[174:175]
	s_nop 0
	v_fma_f32 v148, v146, s48, -v150
	v_fmac_f32_e32 v148, 0xb102e308, v146
	v_pk_add_f32 v[146:147], v[150:151], v[148:149]
	s_nop 0
	v_sub_f32_e32 v149, v147, v149
	v_sub_f32_e32 v149, v151, v149
	v_add_f32_e32 v153, v152, v149
	v_mov_b32_e32 v152, v150
	v_pk_add_f32 v[150:151], v[146:147], v[150:151] neg_lo:[0,1] neg_hi:[0,1]
	v_pk_add_f32 v[154:155], v[146:147], v[152:153]
	v_mov_b32_e32 v149, v146
	v_mov_b32_e32 v151, v155
	v_pk_add_f32 v[156:157], v[148:149], v[150:151] neg_lo:[0,1] neg_hi:[0,1]
	v_pk_add_f32 v[148:149], v[148:149], v[150:151]
	v_mov_b32_e32 v152, v153
	v_pk_add_f32 v[150:151], v[148:149], v[146:147] op_sel:[1,0] op_sel_hi:[0,1] neg_lo:[0,1] neg_hi:[0,1]
	v_pk_add_f32 v[158:159], v[154:155], v[150:151] op_sel_hi:[1,0] neg_lo:[0,1] neg_hi:[0,1]
	v_mov_b32_e32 v154, v155
	v_mov_b32_e32 v155, v149
	v_pk_mov_b32 v[150:151], v[146:147], v[150:151] op_sel:[1,0]
	v_mov_b32_e32 v153, v146
	v_pk_add_f32 v[150:151], v[154:155], v[150:151] neg_lo:[0,1] neg_hi:[0,1]
	v_mov_b32_e32 v158, v156
	v_pk_add_f32 v[146:147], v[152:153], v[150:151] neg_lo:[0,1] neg_hi:[0,1]
	v_mov_b32_e32 v157, v149
	v_pk_add_f32 v[150:151], v[158:159], v[146:147]
	s_nop 0
	v_pk_add_f32 v[152:153], v[150:151], v[150:151] op_sel:[0,1] op_sel_hi:[1,0]
	s_nop 0
	v_pk_add_f32 v[148:149], v[148:149], v[152:153] op_sel:[1,0] op_sel_hi:[0,1]
	v_mov_b32_e32 v151, v148
	v_pk_add_f32 v[154:155], v[150:151], v[156:157] neg_lo:[0,1] neg_hi:[0,1]
	v_mov_b32_e32 v147, v152
	v_sub_f32_e32 v149, v150, v154
	v_pk_add_f32 v[146:147], v[146:147], v[154:155] neg_lo:[0,1] neg_hi:[0,1]
	v_sub_f32_e32 v149, v156, v149
	v_add_f32_e32 v146, v146, v149
	v_add_f32_e32 v146, v146, v147
	v_add_f32_e32 v146, v148, v146
	v_cndmask_b32_e32 v146, v184, v146, vcc
	v_cmp_lt_f32_e64 vcc, |v160|, s49
	s_nop 1
	v_cndmask_b32_e32 v146, v146, v160, vcc
	s_branch .LBB0_306
